# code placement: K-loop body head and both attention tile-loop heads aligned to 64 B
# speedup vs baseline: 1.0061x; 1.0061x over previous
.LBB0_419:
	s_mov_b64 s[6:7], s[16:17]
	.p2align	6

.LBB0_1356:
	s_add_i32 s2, s28, -1
	s_cmp_ge_i32 s2, s69
	s_cbranch_scc1 .LBB0_1358
	s_cmp_gt_u32 s29, 5
	s_cselect_b32 s3, s77, 0
	s_add_i32 s3, s3, s28
	s_lshl_b32 s3, s3, 6
	s_add_i32 s3, s3, s72
	s_sub_i32 s3, s3, 64
	s_mul_hi_i32 s51, s3, s39
	s_mul_i32 s50, s3, s39
	s_and_b32 s2, s2, 3
	s_lshl_b64 s[50:51], s[50:51], 1
	s_mul_i32 s3, s2, 0x3000
	v_lshl_add_u64 v[80:81], v[190:191], 0, s[50:51]
	s_add_i32 s3, s3, s87
	s_mov_b32 s54, m0
	s_mov_b32 m0, s3
	s_nop 0
	global_load_lds_dwordx4 v[80:81], off
	s_mov_b32 m0, s54
	s_lshl_b32 s2, s2, 13
	v_lshl_add_u64 v[80:81], v[114:115], 0, s[50:51]
	s_add_i32 s2, s2, s83
	s_mov_b32 s3, m0
	s_mov_b32 m0, s2
	s_nop 0
	global_load_lds_dwordx4 v[80:81], off
	s_mov_b32 m0, s3
	.p2align	6

.LBB0_1439:
	s_add_i32 s28, s28, 2
	s_and_b64 vcc, exec, s[8:9]
	s_addk_i32 s29, 0x4000
	s_cbranch_vccz .LBB0_1487
	.p2align	6
